# plus: gridDim hidden-arg loads hoisted out of the item loops; GEMM prologue issues both stage batches before the first wait
# baseline (speedup 1.0000x reference)
; #define LAS __attribute__((address_space(3)))
; __global__ void __launch_bounds__(512, 2) mega(Args a_) {
;     extern __shared__ __attribute__((aligned(16))) unsigned char lds[];
;     LAS unsigned char* lds3 = (LAS unsigned char*)lds;
;     KA ap = (KA)__builtin_amdgcn_kernarg_segment_ptr();
;     const int ph_hi = ap->ph_hi;
;     volatile LAS unsigned* xb_st = (volatile LAS unsigned*)(lds3 + (LDS_BYTES - 16));
;     if (threadIdx.x == 0) { xb_st[0] = 0u; xb_st[1] = 0u; }
;     __syncthreads();
;     XcdBarrier xbar = xcd_barrier_post((unsigned*)(ap->ws + WS_CTL) + 64, xb_st);
;     for (int ph = ap->ph_lo; ph < ph_hi; ++ph) {
;         const int layer = ph / 10, k = ph % 10;
;         KA a = ap; asm volatile("" : "+s"(a));
;         int tid = threadIdx.x; asm volatile("" : "+v"(tid));
;         int bid = blockIdx.x; asm volatile("" : "+s"(bid));
;         unsigned char* ws = a->ws;
;         const float* xin = layer == 0 ? a->in[0] : a->out;
.LBB0_5:
	s_or_b64 exec, exec, s[4:5]
	v_readlane_b32 s4, v254, 0
	v_readlane_b32 s5, v254, 1
	s_load_dword s33, s[4:5], 0xb8
	v_readlane_b32 s4, v254, 2
	s_waitcnt lgkmcnt(0)
	s_cmp_ge_i32 s33, s4
	s_cbranch_scc1 .LBB0_506
	v_readlane_b32 s4, v254, 0
	v_readlane_b32 s5, v254, 1
	s_add_u32 s94, s4, 0xc0
	s_addc_u32 s95, s5, 0
	s_load_dword s98, s[94:95], 0x0
	s_load_dword s99, s[94:95], 0x10
	s_waitcnt lgkmcnt(0)
	v_readlane_b32 s4, v254, 2
	s_cmp_lt_i32 s4, 0
	s_cselect_b64 s[4:5], -1, 0
	s_add_u32 s20, s0, 0x500300
	s_addc_u32 s21, s1, 0
	s_add_u32 s92, s0, 0x500500
	v_writelane_b32 v254, s4, 5
	s_addc_u32 s93, s1, 0
	v_lshrrev_b32_e32 v1, 20, v0
	v_writelane_b32 v254, s5, 6
	s_add_u32 s4, s0, 0x500600
	s_addc_u32 s5, s1, 0
	v_writelane_b32 v254, s4, 7
	v_lshrrev_b32_e32 v0, 10, v0
	v_or_b32_e32 v0, v0, v1
	v_writelane_b32 v254, s5, 8
	s_add_u32 s4, s0, 0x500700
	s_addc_u32 s5, s1, 0
	v_writelane_b32 v254, s4, 9
	v_mov_b32_e32 v1, 0
	v_mbcnt_lo_u32_b32 v2, -1, 0
	v_writelane_b32 v254, s5, 10
	s_add_u32 s4, s0, 0x500800
	s_addc_u32 s5, s1, 0
	v_writelane_b32 v254, s4, 11
	v_mov_b32_e32 v227, 0x358637bd
	v_mov_b32_e32 v228, 0x3ecc95a3
	v_writelane_b32 v254, s5, 12
	s_add_u32 s4, s0, 0x500900
	s_addc_u32 s5, s1, 0
	v_writelane_b32 v254, s4, 13
	v_mov_b32_e32 v229, 0x260
	v_mov_b32_e32 v230, 1
	v_writelane_b32 v254, s5, 14
	s_add_u32 s4, s0, 0x500a00
	s_addc_u32 s5, s1, 0
	v_writelane_b32 v254, s4, 15
	v_mov_b32_e32 v231, 0x98
	v_mov_b32_e32 v232, 0x90
	v_writelane_b32 v254, s5, 16
	s_add_u32 s4, s0, 0x500b00
	s_addc_u32 s5, s1, 0
	v_writelane_b32 v254, s4, 17
	v_mbcnt_hi_u32_b32 v233, -1, v2
	v_mov_b64_e32 v[186:187], 0x200
	v_writelane_b32 v254, s5, 18
	s_add_u32 s4, s0, 0x500c00
	s_addc_u32 s5, s1, 0
	v_writelane_b32 v254, s4, 19
	v_mov_b64_e32 v[188:189], 0x1ff
	v_mov_b32_e32 v234, 0x7f800000
	v_writelane_b32 v254, s5, 20
	s_add_u32 s4, s0, 0x500d00
	s_addc_u32 s5, s1, 0
	v_writelane_b32 v254, s4, 21
	v_mov_b32_e32 v190, 0x3f317218
	v_mov_b32_e32 v235, 0x9800000
	v_writelane_b32 v254, s5, 22
	s_add_u32 s4, s0, 0x500e00
	s_addc_u32 s5, s1, 0
	v_writelane_b32 v254, s4, 23
	v_mov_b32_e32 v238, v1
	v_mov_b32_e32 v239, v1
	v_writelane_b32 v254, s5, 24
	s_add_u32 s4, s0, 0x500f00
	s_addc_u32 s5, s1, 0
	v_writelane_b32 v254, s4, 25
	v_mov_b32_e32 v240, v1
	v_mov_b32_e32 v241, v1
	v_writelane_b32 v254, s5, 26
	s_add_u32 s4, s0, 0x501000
	s_addc_u32 s5, s1, 0
	v_writelane_b32 v254, s4, 27
	v_mov_b64_e32 v[194:195], 0xa00
	v_mov_b64_e32 v[196:197], 0x9ff
	v_writelane_b32 v254, s5, 28
	s_add_u32 s4, s0, 0x501100
	s_addc_u32 s5, s1, 0
	v_writelane_b32 v254, s4, 29
	s_movk_i32 s22, 0x3fff
	s_movk_i32 s23, 0x1000
	v_writelane_b32 v254, s5, 30
	s_add_u32 s4, s0, 0x501200
	s_addc_u32 s5, s1, 0
	s_add_u32 s36, s0, 0x501300
	s_addc_u32 s37, s1, 0
	s_add_u32 s38, s0, 0x501400
	s_addc_u32 s39, s1, 0
	v_writelane_b32 v254, s4, 31
	s_cmp_eq_u32 s8, 15
	s_mov_b32 s24, 0x800000
	v_writelane_b32 v254, s5, 32
	s_cselect_b64 s[4:5], -1, 0
	v_writelane_b32 v254, s4, 33
	s_cmp_eq_u32 s8, 14
	s_movk_i32 s34, 0x110
	v_writelane_b32 v254, s5, 34
	s_cselect_b64 s[4:5], -1, 0
	v_writelane_b32 v254, s4, 35
	s_cmp_eq_u32 s8, 13
	s_mov_b32 s25, 0xf800000
	v_writelane_b32 v254, s5, 36
	s_cselect_b64 s[4:5], -1, 0
	v_writelane_b32 v254, s4, 37
	s_cmp_eq_u32 s8, 12
	s_movk_i32 s26, 0x1800
	v_writelane_b32 v254, s5, 38
	s_cselect_b64 s[4:5], -1, 0
	v_writelane_b32 v254, s4, 39
	s_cmp_eq_u32 s8, 11
	s_mov_b32 s27, 0xa040
	v_writelane_b32 v254, s5, 40
	s_cselect_b64 s[4:5], -1, 0
	v_writelane_b32 v254, s4, 41
	s_cmp_eq_u32 s8, 10
	s_mov_b32 s89, 0
	v_writelane_b32 v254, s5, 42
	s_cselect_b64 s[4:5], -1, 0
	v_writelane_b32 v254, s4, 43
	s_cmp_eq_u32 s8, 9
	s_mov_b64 s[96:97], 0x80
	v_writelane_b32 v254, s5, 44
	s_cselect_b64 s[4:5], -1, 0
	v_writelane_b32 v254, s4, 45
	s_cmp_eq_u32 s8, 8
	s_nop 0
	v_writelane_b32 v254, s5, 46
	s_cselect_b64 s[4:5], -1, 0
	v_writelane_b32 v254, s4, 47
	s_cmp_eq_u32 s8, 7
	s_nop 0
	v_writelane_b32 v254, s5, 48
	s_cselect_b64 s[4:5], -1, 0
	v_writelane_b32 v254, s4, 49
	s_cmp_eq_u32 s8, 6
	s_nop 0
	v_writelane_b32 v254, s5, 50
	s_cselect_b64 s[4:5], -1, 0
	v_writelane_b32 v254, s4, 51
	s_cmp_eq_u32 s8, 5
	s_nop 0
	v_writelane_b32 v254, s5, 52
	s_cselect_b64 s[4:5], -1, 0
	v_writelane_b32 v254, s4, 53
	s_cmp_eq_u32 s8, 4
	s_nop 0
	v_writelane_b32 v254, s5, 54
	s_cselect_b64 s[4:5], -1, 0
	v_writelane_b32 v254, s4, 55
	s_cmp_eq_u32 s8, 3
	s_nop 0
	v_writelane_b32 v254, s5, 56
	s_cselect_b64 s[4:5], -1, 0
	v_writelane_b32 v254, s4, 57
	s_cmp_eq_u32 s8, 2
	s_nop 0
	v_writelane_b32 v254, s5, 58
	s_cselect_b64 s[4:5], -1, 0
	v_writelane_b32 v254, s4, 59
	s_cmp_eq_u32 s8, 1
	s_nop 0
	v_writelane_b32 v254, s5, 60
	s_cselect_b64 s[4:5], -1, 0
	v_writelane_b32 v254, s4, 61
	s_cmp_eq_u32 s8, 0
	s_nop 0
	v_writelane_b32 v254, s5, 62
	s_cselect_b64 s[4:5], -1, 0
	v_writelane_b32 v254, s4, 63
	s_nop 1
	v_writelane_b32 v255, s5, 0
	s_lshl_b32 s4, s8, 8
	s_add_u32 s2, s2, s4
	s_addc_u32 s3, s3, 0
	s_add_u32 s4, s2, 0x1400
	s_addc_u32 s5, s3, 0
	v_writelane_b32 v255, s4, 1
	s_add_u32 s2, s2, 0x2400
	s_addc_u32 s3, s3, 0
	v_writelane_b32 v255, s5, 2
	v_writelane_b32 v255, s2, 3
	s_nop 1
	v_writelane_b32 v255, s3, 4
	s_add_u32 s2, s0, 0x503500
	s_addc_u32 s3, s1, 0
	v_writelane_b32 v255, s2, 5
	s_add_u32 s0, s0, 0x503600
	s_addc_u32 s1, s1, 0
	v_writelane_b32 v255, s3, 6
	v_writelane_b32 v255, s0, 7
	s_nop 1
	v_writelane_b32 v255, s1, 8
	s_movk_i32 s0, 0x3ff
	v_and_or_b32 v0, v0, s0, v226
	s_add_i32 s0, 0, 0x15c00
	v_writelane_b32 v255, s0, 9
	s_add_i32 s0, 0, 0x16400
	v_writelane_b32 v255, s0, 10
	s_add_i32 s0, 0, 0x10800
	v_writelane_b32 v255, s0, 11
	s_add_i32 s0, 0, 0x14c00
	v_writelane_b32 v255, s0, 12
	s_add_i32 s0, 0, 0x16600
	v_writelane_b32 v255, s0, 13
	s_add_i32 s0, 0, 0x10d00
	v_writelane_b32 v255, s0, 14
	s_add_i32 s0, 0, 0x4400
	v_writelane_b32 v255, s0, 15
	s_add_i32 s0, 0, 0x1f600
	v_writelane_b32 v255, s0, 16
	s_add_i32 s0, 0, 0x1d000
	v_writelane_b32 v255, s0, 17
	s_add_i32 s0, 0, 0x1d100
	v_writelane_b32 v255, s0, 18
	s_add_i32 s0, 0, 0x1d200
	v_writelane_b32 v255, s0, 19
	s_add_i32 s0, 0, 0x1d0fc
	v_writelane_b32 v255, s0, 20
	s_add_i32 s0, 0, 0x20ff0
	v_writelane_b32 v255, s0, 21
	s_add_i32 s0, 0, 0x20ff4
	v_writelane_b32 v255, s0, 22
	v_cmp_eq_u32_e64 s[0:1], 0, v0
	s_nop 1
	v_writelane_b32 v255, s0, 23
	s_nop 1
	v_writelane_b32 v255, s1, 24
	v_writelane_b32 v255, s20, 25
	s_mov_b64 s[0:1], 0x20000
	s_nop 0
	v_writelane_b32 v255, s21, 26
	s_branch .LBB0_10

; #define PG8_STAGE(bufoff, gbase, voff) do { _Pragma("unroll") for (int _i = 0; _i < 2; ++_i) \
;         __builtin_amdgcn_global_load_lds((const unsigned*)((const char*)(gbase) + (voff)[_i]), (LAS unsigned*)(lds + (bufoff) + ldsw + _i * 8192), 16, 0, 0); } while (0)
; #define PG8_WAIT_V(n) asm volatile("s_waitcnt vmcnt(" #n ")" ::: "memory")
; #define PG8_BAR __builtin_amdgcn_s_barrier()
; template <class Epi, class Sched, bool ALIGN_EPI = false, bool SP2 = false>
; __device__ __forceinline__ void gemm_phase(LAS unsigned char* lds, const Gemm g, const Sched& S, const Epi& E, const int tid_) {
;     ...
;     if constexpr (SP2) {
;         PG8_STAGE(PG8_SB(0, 0), cB, voffB); PG8_STAGE(PG8_SB(0, 1), cB + hstep, voffB); PG8_STAGE(PG8_SA(0, 0), cA, voffA); PG8_STAGE(PG8_SA(0, 1), cA + hstep, voffA);
;         if (wr == 1) PG8_BAR;
;         PG8_WAIT_V(2); PG8_BAR;
;         PG8_STAGE(PG8_SB(1, 0), cB + kstep, voffB); PG8_STAGE(PG8_SA(1, 0), cA + kstep, voffA); PG8_STAGE(PG8_SB(1, 1), cB + hstep + kstep, voffB);
;         PG8_WAIT_V(6); PG8_BAR;
.LBB0_23:
	v_lshrrev_b32_e32 v17, 1, v198
	v_and_b32_e32 v17, 24, v17
	v_and_b32_e32 v16, 15, v198
	v_lshlrev_b32_e32 v18, 1, v17
	s_sext_i32_i16 s20, s10
	s_add_u32 s10, s4, 0xd800000
	v_lshl_or_b32 v142, s13, 6, v16
	v_lshl_or_b32 v16, v16, 6, v18
	v_lshlrev_b32_e32 v18, 2, v198
	s_addc_u32 s11, s5, 0
	s_lshl_b32 s13, s13, 13
	v_and_b32_e32 v18, 32, v18
	v_bitop3_b32 v19, v16, s13, v18 bitop3:0xde
	s_lshl_b32 s13, s14, 5
	s_and_b32 s16, s13, 0x60
	s_add_i32 m0, s45, 0x18000
	v_lshl_add_u64 v[8:9], v[8:9], 0, s[96:97]
	s_lshl_b32 s13, s16, 7
	s_nop 0
	global_load_lds_dwordx4 v[8:9], off
	v_lshl_add_u64 v[6:7], v[6:7], 0, s[96:97]
	s_add_i32 m0, s45, 0x1a000
	s_add_i32 s60, s45, 0x8000
	s_add_i32 s61, s45, 0xa000
	global_load_lds_dwordx4 v[6:7], off
	v_lshl_add_u64 v[2:3], v[2:3], 0, s[96:97]
	s_mov_b32 m0, s60
	s_add_u32 s14, s48, 0x80080
	global_load_lds_dwordx4 v[2:3], off
	v_lshl_add_u64 v[2:3], v[4:5], 0, s[96:97]
	s_mov_b32 m0, s61
	s_addc_u32 s15, s49, 0
	global_load_lds_dwordx4 v[2:3], off
	s_add_i32 m0, s45, 0x1c000
	v_lshl_add_u64 v[2:3], s[14:15], 0, v[0:1]
	global_load_lds_dwordx4 v[2:3], off
	v_lshl_add_u64 v[2:3], s[14:15], 0, v[134:135]
	s_add_i32 m0, s45, 0x1e000
	s_cmpk_lt_u32 s12, 0x100
	global_load_lds_dwordx4 v[2:3], off
	s_waitcnt vmcnt(8)
	s_barrier
	v_lshlrev_b32_e32 v2, 15, v10
	v_and_b32_e32 v2, 0xffff0000, v2
	v_lshl_add_u32 v2, v11, 12, v2
	v_and_b32_e32 v3, 1, v10
	v_lshl_or_b32 v2, v3, 6, v2
	v_lshl_add_u32 v136, v12, 1, v2
	v_lshlrev_b32_e32 v2, 15, v13
	v_and_b32_e32 v2, 0xffff0000, v2
	s_waitcnt vmcnt(6)
	v_lshl_add_u32 v2, v14, 12, v2
	v_and_b32_e32 v3, 1, v13
	v_lshl_or_b32 v2, v3, 6, v2
	v_bitop3_b32 v143, s13, v16, v18 bitop3:0xf6
	s_cselect_b64 s[12:13], -1, 0
	s_waitcnt lgkmcnt(0)
	s_ashr_i32 s62, s59, 31
	v_or_b32_e32 v144, s16, v17
	v_mov_b32_e32 v137, v1
	v_lshl_add_u32 v138, v15, 1, v2
	v_mov_b32_e32 v139, v1
	s_mov_b32 s63, 0
	v_add_u32_e32 v145, 0, v19
	s_barrier
	s_branch .LBB0_27

; #define PG8_STAGE(bufoff, gbase, voff) do { _Pragma("unroll") for (int _i = 0; _i < 2; ++_i) \
;         __builtin_amdgcn_global_load_lds((const unsigned*)((const char*)(gbase) + (voff)[_i]), (LAS unsigned*)(lds + (bufoff) + ldsw + _i * 8192), 16, 0, 0); } while (0)
; #define PG8_WAIT_V(n) asm volatile("s_waitcnt vmcnt(" #n ")" ::: "memory")
; #define PG8_BAR __builtin_amdgcn_s_barrier()
; template <class Epi, class Sched, bool ALIGN_EPI = false, bool SP2 = false>
; __device__ __forceinline__ void gemm_phase(LAS unsigned char* lds, const Gemm g, const Sched& S, const Epi& E, const int tid_) {
;     ...
;     if constexpr (SP2) {
;         PG8_STAGE(PG8_SB(0, 0), cB, voffB); PG8_STAGE(PG8_SB(0, 1), cB + hstep, voffB); PG8_STAGE(PG8_SA(0, 0), cA, voffA); PG8_STAGE(PG8_SA(0, 1), cA + hstep, voffA);
;         if (wr == 1) PG8_BAR;
;         PG8_WAIT_V(2); PG8_BAR;
;         PG8_STAGE(PG8_SB(1, 0), cB + kstep, voffB); PG8_STAGE(PG8_SA(1, 0), cA + kstep, voffA); PG8_STAGE(PG8_SB(1, 1), cB + hstep + kstep, voffB);
;         PG8_WAIT_V(6); PG8_BAR;
.LBB0_60:
	v_bfe_u32 v18, v198, 4, 2
	v_and_b32_e32 v19, 15, v198
	v_lshlrev_b32_e32 v20, 4, v18
	v_lshl_or_b32 v156, s14, 6, v19
	v_lshl_or_b32 v19, v19, 6, v20
	v_lshlrev_b32_e32 v20, 2, v198
	s_sext_i32_i8 s20, s12
	s_lshl_b32 s12, s14, 13
	v_and_b32_e32 v20, 32, v20
	v_bitop3_b32 v21, v19, s12, v20 bitop3:0xde
	s_lshl_b32 s12, s15, 5
	s_and_b32 s16, s12, 0x60
	s_add_i32 m0, s45, 0x18000
	v_lshl_add_u64 v[8:9], v[8:9], 0, s[96:97]
	s_lshl_b32 s12, s16, 7
	s_nop 0
	global_load_lds_dwordx4 v[8:9], off
	v_lshl_add_u64 v[6:7], v[6:7], 0, s[96:97]
	s_add_i32 m0, s45, 0x1a000
	s_add_i32 s62, s45, 0x8000
	s_add_i32 s63, s45, 0xa000
	global_load_lds_dwordx4 v[6:7], off
	v_lshl_add_u64 v[2:3], v[2:3], 0, s[96:97]
	s_mov_b32 m0, s62
	s_add_u32 s14, s48, 0x80080
	global_load_lds_dwordx4 v[2:3], off
	v_lshl_add_u64 v[2:3], v[4:5], 0, s[96:97]
	s_mov_b32 m0, s63
	s_addc_u32 s15, s49, 0
	global_load_lds_dwordx4 v[2:3], off
	s_add_i32 m0, s45, 0x1c000
	v_lshl_add_u64 v[2:3], s[14:15], 0, v[0:1]
	global_load_lds_dwordx4 v[2:3], off
	v_lshl_add_u64 v[2:3], s[14:15], 0, v[142:143]
	s_add_i32 m0, s45, 0x1e000
	s_mov_b64 s[14:15], 0x80080
	global_load_lds_dwordx4 v[2:3], off
	s_waitcnt vmcnt(8)
	s_barrier
	v_lshlrev_b32_e32 v2, 14, v10
	v_and_b32_e32 v2, 0x7fff8000, v2
	v_lshl_add_u32 v2, v11, 11, v2
	v_or_b32_e32 v2, v2, v12
	v_add_lshl_u32 v2, v2, v13, 1
	v_mov_b32_e32 v3, v1
	v_lshl_add_u64 v[144:145], v[2:3], 0, s[14:15]
	v_lshlrev_b32_e32 v2, 14, v14
	v_and_b32_e32 v2, 0x7fff8000, v2
	v_lshl_add_u32 v2, v15, 11, v2
	s_waitcnt vmcnt(6)
	v_or_b32_e32 v2, v2, v16
	s_cmpk_lt_u32 s13, 0x100
	v_add_lshl_u32 v2, v2, v17, 1
	s_waitcnt vmcnt(0)
	v_bitop3_b32 v157, s12, v19, v20 bitop3:0xf6
	s_cselect_b64 s[12:13], -1, 0
	s_waitcnt lgkmcnt(0)
	s_ashr_i32 s64, s61, 31
	v_lshl_or_b32 v158, v18, 2, s16
	v_lshl_add_u64 v[146:147], v[2:3], 0, s[14:15]
	s_mov_b32 s65, 0
	v_add_u32_e32 v159, 0, v21
	s_barrier
	s_branch .LBB0_63

; #define PG8_STAGE(bufoff, gbase, voff) do { _Pragma("unroll") for (int _i = 0; _i < 2; ++_i) \
;         __builtin_amdgcn_global_load_lds((const unsigned*)((const char*)(gbase) + (voff)[_i]), (LAS unsigned*)(lds + (bufoff) + ldsw + _i * 8192), 16, 0, 0); } while (0)
; #define PG8_WAIT_V(n) asm volatile("s_waitcnt vmcnt(" #n ")" ::: "memory")
; #define PG8_BAR __builtin_amdgcn_s_barrier()
; template <class Epi, class Sched, bool ALIGN_EPI = false, bool SP2 = false>
; __device__ __forceinline__ void gemm_phase(LAS unsigned char* lds, const Gemm g, const Sched& S, const Epi& E, const int tid_) {
;     ...
;     if constexpr (SP2) {
;         PG8_STAGE(PG8_SB(0, 0), cB, voffB); PG8_STAGE(PG8_SB(0, 1), cB + hstep, voffB); PG8_STAGE(PG8_SA(0, 0), cA, voffA); PG8_STAGE(PG8_SA(0, 1), cA + hstep, voffA);
;         if (wr == 1) PG8_BAR;
;         PG8_WAIT_V(2); PG8_BAR;
;         PG8_STAGE(PG8_SB(1, 0), cB + kstep, voffB); PG8_STAGE(PG8_SA(1, 0), cA + kstep, voffA); PG8_STAGE(PG8_SB(1, 1), cB + hstep + kstep, voffB);
;         PG8_WAIT_V(6); PG8_BAR;
.LBB0_86:
	s_sext_i32_i8 s68, s12
	s_add_u32 s12, s4, 0x19800000
	s_addc_u32 s13, s5, 0
	v_lshlrev_b32_e32 v11, 2, v173
	s_lshl_b32 s15, s15, 5
	s_add_i32 m0, s49, 0x18000
	v_lshl_add_u64 v[8:9], v[8:9], 0, s[96:97]
	v_lshl_or_b32 v176, s16, 6, v173
	v_lshl_or_b32 v10, v173, 6, v174
	s_lshl_b32 s16, s16, 13
	v_and_b32_e32 v11, 32, v11
	s_and_b32 s18, s15, 0x60
	s_nop 0
	global_load_lds_dwordx4 v[8:9], off
	v_lshl_add_u64 v[6:7], v[6:7], 0, s[96:97]
	s_add_i32 m0, s49, 0x1a000
	s_add_i32 s64, s49, 0x8000
	s_add_i32 s65, s49, 0xa000
	v_bitop3_b32 v10, v10, s16, v11 bitop3:0xde
	global_load_lds_dwordx4 v[6:7], off
	v_lshl_add_u64 v[2:3], v[2:3], 0, s[96:97]
	s_mov_b32 m0, s64
	s_add_u32 s16, s54, 0x40080
	global_load_lds_dwordx4 v[2:3], off
	v_lshl_add_u64 v[2:3], v[4:5], 0, s[96:97]
	s_mov_b32 m0, s65
	s_addc_u32 s17, s55, 0
	global_load_lds_dwordx4 v[2:3], off
	s_add_i32 m0, s49, 0x1c000
	v_lshl_add_u64 v[2:3], s[16:17], 0, v[0:1]
	global_load_lds_dwordx4 v[2:3], off
	v_lshl_add_u64 v[2:3], s[16:17], 0, v[204:205]
	s_add_i32 m0, s49, 0x1e000
	s_cmpk_lt_u32 s14, 0x100
	global_load_lds_dwordx4 v[2:3], off
	s_waitcnt vmcnt(8)
	s_barrier
	v_lshlrev_b32_e32 v2, 14, v166
	v_and_b32_e32 v2, 0xffff8000, v2
	v_lshl_add_u32 v2, v167, 11, v2
	v_and_b32_e32 v3, 1, v166
	v_lshl_or_b32 v2, v3, 6, v2
	v_lshl_add_u32 v150, v168, 1, v2
	v_lshlrev_b32_e32 v2, 14, v169
	v_and_b32_e32 v2, 0xffff8000, v2
	s_waitcnt vmcnt(6)
	v_lshl_add_u32 v2, v170, 11, v2
	v_and_b32_e32 v3, 1, v169
	v_lshl_or_b32 v2, v3, 6, v2
	v_lshl_or_b32 v177, s18, 7, v175
	s_cselect_b64 s[14:15], -1, 0
	s_waitcnt lgkmcnt(0)
	s_ashr_i32 s66, s7, 31
	v_or_b32_e32 v178, s18, v172
	v_mov_b32_e32 v151, v1
	v_lshl_add_u32 v152, v171, 1, v2
	v_mov_b32_e32 v153, v1
	s_mov_b32 s67, 0
	v_add_u32_e32 v179, 0, v10
	s_barrier
	s_branch .LBB0_89

; #define PG8_STAGE(bufoff, gbase, voff) do { _Pragma("unroll") for (int _i = 0; _i < 2; ++_i) \
;         __builtin_amdgcn_global_load_lds((const unsigned*)((const char*)(gbase) + (voff)[_i]), (LAS unsigned*)(lds + (bufoff) + ldsw + _i * 8192), 16, 0, 0); } while (0)
; #define PG8_WAIT_V(n) asm volatile("s_waitcnt vmcnt(" #n ")" ::: "memory")
; #define PG8_BAR __builtin_amdgcn_s_barrier()
; template <class Epi, class Sched, bool ALIGN_EPI = false, bool SP2 = false>
; __device__ __forceinline__ void gemm_phase(LAS unsigned char* lds, const Gemm g, const Sched& S, const Epi& E, const int tid_) {
;     ...
;     if constexpr (SP2) {
;         PG8_STAGE(PG8_SB(0, 0), cB, voffB); PG8_STAGE(PG8_SB(0, 1), cB + hstep, voffB); PG8_STAGE(PG8_SA(0, 0), cA, voffA); PG8_STAGE(PG8_SA(0, 1), cA + hstep, voffA);
;         if (wr == 1) PG8_BAR;
;         PG8_WAIT_V(2); PG8_BAR;
;         PG8_STAGE(PG8_SB(1, 0), cB + kstep, voffB); PG8_STAGE(PG8_SA(1, 0), cA + kstep, voffA); PG8_STAGE(PG8_SB(1, 1), cB + hstep + kstep, voffB);
;         PG8_WAIT_V(6); PG8_BAR;
.LBB0_110:
	s_add_u32 s10, s4, 0x19801000
	s_addc_u32 s11, s5, 0
	s_lshl_b32 s15, s15, 5
	s_add_i32 m0, s47, 0x18000
	v_lshl_add_u64 v[8:9], v[8:9], 0, s[96:97]
	s_lshl_b32 s18, s14, 13
	s_and_b32 s15, s15, 0x60
	s_nop 0
	global_load_lds_dwordx4 v[8:9], off
	v_lshl_add_u64 v[6:7], v[6:7], 0, s[96:97]
	s_add_i32 m0, s47, 0x1a000
	s_add_i32 s62, s47, 0x8000
	s_add_i32 s63, s47, 0xa000
	global_load_lds_dwordx4 v[6:7], off
	v_lshl_add_u64 v[2:3], v[2:3], 0, s[96:97]
	s_mov_b32 m0, s62
	s_add_u32 s16, s50, 0x40080
	global_load_lds_dwordx4 v[2:3], off
	v_lshl_add_u64 v[2:3], v[4:5], 0, s[96:97]
	s_mov_b32 m0, s63
	s_addc_u32 s17, s51, 0
	global_load_lds_dwordx4 v[2:3], off
	s_add_i32 m0, s47, 0x1c000
	v_lshl_add_u64 v[2:3], s[16:17], 0, v[0:1]
	global_load_lds_dwordx4 v[2:3], off
	v_lshl_add_u64 v[2:3], s[16:17], 0, v[204:205]
	s_add_i32 m0, s47, 0x1e000
	v_and_b32_e32 v4, 1, v166
	global_load_lds_dwordx4 v[2:3], off
	s_waitcnt vmcnt(8)
	s_barrier
	v_lshlrev_b32_e32 v3, 2, v173
	v_lshl_or_b32 v2, v173, 6, v174
	v_and_b32_e32 v3, 32, v3
	v_bitop3_b32 v2, v2, s18, v3 bitop3:0xde
	v_lshlrev_b32_e32 v3, 14, v166
	v_and_b32_e32 v3, 0xffff8000, v3
	v_lshl_add_u32 v3, v167, 11, v3
	v_lshl_or_b32 v3, v4, 6, v3
	v_lshl_add_u32 v206, v168, 1, v3
	v_lshlrev_b32_e32 v3, 14, v169
	v_and_b32_e32 v3, 0xffff8000, v3
	s_waitcnt vmcnt(6)
	v_lshl_add_u32 v3, v170, 11, v3
	v_and_b32_e32 v4, 1, v169
	s_cmpk_lt_u32 s13, 0x100
	v_lshl_or_b32 v3, v4, 6, v3
	s_sext_i32_i8 s20, s12
	v_lshl_or_b32 v191, s14, 6, v173
	v_lshl_or_b32 v199, s15, 7, v175
	s_cselect_b64 s[12:13], -1, 0
	s_ashr_i32 s64, s7, 31
	v_or_b32_e32 v236, s15, v172
	v_mov_b32_e32 v207, v1
	v_lshl_add_u32 v208, v171, 1, v3
	v_mov_b32_e32 v209, v1
	s_mov_b32 s65, 0
	v_add_u32_e32 v237, 0, v2
	s_barrier
	s_branch .LBB0_113

; __device__ __forceinline__ void unpack8(const u32x4 w, float* f) { f[0] = bflo(w.x); f[1] = bfhi(w.x); f[2] = bflo(w.y); f[3] = bfhi(w.y); f[4] = bflo(w.z); f[5] = bfhi(w.z); f[6] = bflo(w.w); f[7] = bfhi(w.w); }
; __device__ __forceinline__ float gelu_tanh(float x) { const float u = 0.7978845608028654f * (x + 0.044715f * x * x * x); return x * sigmoidf_(2.0f * u); }
; template <bool P3>
; __device__ __forceinline__ void lru_pass(KA a, int layer, unsigned char* lds, const int tid_, const int bid_) {
;     ...
;             if (P3) {
;                 float h = 0.f;
; #pragma unroll
;                 for (int part = 0; part < 4; ++part) h = CP[(part * 128 + chl) * 2] * h + CP[(part * 128 + chl) * 2 + 1];
; #pragma unroll
;                 for (int s2 = 0; s2 < 3; ++s2) { if (s2 < seg) h = SEG[(s2 * 128 + chl) * 2] * h + SEG[(s2 * 128 + chl) * 2 + 1]; }
; #pragma unroll
;                 for (int t = 0; t < 16; ++t) { h = av[t] * h + bv[t]; XCF[(t0 + t) * 132 + chl] = h; }
;             } else if (tid < 128) {
;                 float h = 0.f, P = 1.f;
; #pragma unroll
;                 for (int s2 = 0; s2 < 4; ++s2) { const float Ps = SEG[(s2 * 128 + tid) * 2], hs = SEG[(s2 * 128 + tid) * 2 + 1]; h = Ps * h + hs; P *= Ps; }
;                 AGGA[(size_t)c * 1024 + n * 128 + tid] = P; AGGB[(size_t)c * 1024 + n * 128 + tid] = h;
;             }
;         }
;         __syncthreads();
;         if (P3) {
;             float y[16], o[16]; unpack8(yr0, y); unpack8(yr1, y + 8);
; #pragma unroll
;             for (int e = 0; e < 16; ++e) o[e] = XCF[tl * 132 + 16 * sub + e] * gelu_tanh(y[e]);
.LBB0_134:
	s_or_b64 exec, exec, s[20:21]
	v_fmac_f32_e32 v78, v79, v47
	v_fmac_f32_e32 v76, v77, v78
	v_fmac_f32_e32 v74, v75, v76
	v_fmac_f32_e32 v70, v71, v74
	v_fmac_f32_e32 v72, v73, v70
	v_fmac_f32_e32 v66, v67, v72
	v_fmac_f32_e32 v68, v69, v66
	v_fmac_f32_e32 v60, v61, v68
	v_fmac_f32_e32 v62, v63, v60
	v_add_u32_e32 v44, 0x400, v144
	v_fmac_f32_e32 v48, v49, v62
	ds_write2_b32 v44, v70, v72 offset0:8 offset1:140
	v_add_u32_e32 v44, 0x800, v144
	v_fmac_f32_e32 v54, v55, v48
	ds_write2_b32 v44, v66, v68 offset0:16 offset1:148
	v_add_u32_e32 v44, 0xc00, v144
	v_fmac_f32_e32 v50, v51, v54
	ds_write2_b32 v44, v60, v62 offset0:24 offset1:156
	v_add_u32_e32 v44, 0x1000, v144
	v_fmac_f32_e32 v56, v57, v50
	ds_write2_b32 v44, v48, v54 offset0:32 offset1:164
	v_add_u32_e32 v44, 0x1400, v144
	v_fmac_f32_e32 v52, v53, v56
	ds_write2_b32 v44, v50, v56 offset0:40 offset1:172
	v_fmac_f32_e32 v58, v59, v52
	v_add_u32_e32 v44, 0x1800, v144
	v_lshlrev_b32_e32 v60, 16, v40
	ds_write2_b32 v44, v52, v58 offset0:48 offset1:180
	v_mul_f32_e32 v44, 0x3d372713, v60
	v_mul_f32_e32 v44, v44, v60
	v_mov_b32_e32 v45, v60
	v_fmac_f32_e32 v45, v44, v45
	v_mul_f32_e32 v44, 0x3f4c422a, v45
	v_add_f32_e32 v44, v44, v44
	v_mul_f32_e32 v44, 0xbfb8aa3b, v44
	v_lshlrev_b32_e32 v62, 16, v41
	v_exp_f32_e32 v44, v44
	v_and_b32_e32 v63, 0xffff0000, v41
	v_mul_f32_e32 v41, 0x3d372713, v62
	v_mul_f32_e32 v41, v41, v62
	v_mov_b32_e32 v53, v62
	v_fmac_f32_e32 v53, v41, v53
	v_and_b32_e32 v61, 0xffff0000, v40
	v_mul_f32_e32 v41, 0x3f4c422a, v53
	v_add_f32_e32 v40, 1.0, v44
	v_mul_f32_e32 v44, 0x3d372713, v61
	v_add_f32_e32 v41, v41, v41
	v_mul_f32_e32 v44, v44, v61
	v_mov_b32_e32 v45, v61
	v_mul_f32_e32 v41, 0xbfb8aa3b, v41
	v_fmac_f32_e32 v45, v44, v45
	v_exp_f32_e32 v53, v41
	v_mul_f32_e32 v41, 0x3d372713, v63
	v_mul_f32_e32 v44, 0x3f4c422a, v45
	v_mul_f32_e32 v41, v41, v63
	v_mov_b32_e32 v54, v63
	v_add_f32_e32 v44, v44, v44
	v_fmac_f32_e32 v54, v41, v54
	v_mul_f32_e32 v44, 0xbfb8aa3b, v44
	v_mul_f32_e32 v41, 0x3f4c422a, v54
	v_exp_f32_e32 v52, v44
	v_add_f32_e32 v41, v41, v41
	v_mul_f32_e32 v41, 0xbfb8aa3b, v41
	v_exp_f32_e32 v54, v41
	v_add_f32_e32 v52, 1.0, v52
	v_fmac_f32_e32 v64, v65, v58
	v_rcp_f32_e32 v40, v40
	v_rcp_f32_e32 v41, v52
	v_add_f32_e32 v52, 1.0, v53
	ds_write_b32 v144, v64 offset:7392
	v_rcp_f32_e32 v64, v52
	v_add_f32_e32 v52, 1.0, v54
	ds_write_b32 v143, v78
	ds_write2_b32 v144, v76, v74 offset1:132
	s_waitcnt lgkmcnt(0)
	s_barrier
; __device__ __forceinline__ void unpack8(const u32x4 w, float* f) { f[0] = bflo(w.x); f[1] = bfhi(w.x); f[2] = bflo(w.y); f[3] = bfhi(w.y); f[4] = bflo(w.z); f[5] = bfhi(w.z); f[6] = bflo(w.w); f[7] = bfhi(w.w); }
; __device__ __forceinline__ u32x4 pack8(const float* f) { u32x4 w; w.x = cvt_pk_bf16(f[0], f[1]); w.y = cvt_pk_bf16(f[2], f[3]); w.z = cvt_pk_bf16(f[4], f[5]); w.w = cvt_pk_bf16(f[6], f[7]); return w; }
; __device__ __forceinline__ float gelu_tanh(float x) { const float u = 0.7978845608028654f * (x + 0.044715f * x * x * x); return x * sigmoidf_(2.0f * u); }
; template <bool P3>
; __device__ __forceinline__ void lru_pass(KA a, int layer, unsigned char* lds, const int tid_, const int bid_) {
;     ...
;     for (int item = bid_; item < 2048; item += gridDim.x) {
;     ...
;         if (P3) {
;             float y[16], o[16]; unpack8(yr0, y); unpack8(yr1, y + 8);
; #pragma unroll
;             for (int e = 0; e < 16; ++e) o[e] = XCF[tl * 132 + 16 * sub + e] * gelu_tanh(y[e]);
;             bf16_t* dst = (bf16_t*)(ws + WS_OL) + (size_t)tg * 1024 + ch0;
;             *(u32x4*)dst = pack8(o); *(u32x4*)(dst + 8) = pack8(o + 8);
;             __syncthreads();
;         }
;     }
	ds_read_b128 v[44:47], v137
	ds_read_b128 v[48:51], v137 offset:16
	v_rcp_f32_e32 v65, v52
	v_pk_mul_f32 v[40:41], v[40:41], v[60:61]
	v_lshlrev_b32_e32 v60, 16, v42
	v_and_b32_e32 v61, 0xffff0000, v42
	v_mul_f32_e32 v42, 0x3d372713, v60
	s_waitcnt lgkmcnt(1)
	v_pk_mul_f32 v[40:41], v[40:41], v[44:45]
	v_pk_mul_f32 v[44:45], v[64:65], v[62:63]
	v_mul_f32_e32 v42, v42, v60
	v_mov_b32_e32 v62, v60
	v_fmac_f32_e32 v62, v42, v62
	v_mul_f32_e32 v42, 0x3f4c422a, v62
	v_mul_f32_e32 v62, 0x3d372713, v61
	v_mul_f32_e32 v62, v62, v61
	v_mov_b32_e32 v63, v61
	v_fmac_f32_e32 v63, v62, v63
	v_add_f32_e32 v42, v42, v42
	v_mul_f32_e32 v62, 0x3f4c422a, v63
	v_mul_f32_e32 v42, 0xbfb8aa3b, v42
	v_add_f32_e32 v62, v62, v62
	v_exp_f32_e32 v42, v42
	v_mul_f32_e32 v62, 0xbfb8aa3b, v62
	v_exp_f32_e32 v62, v62
	v_pk_mul_f32 v[44:45], v[44:45], v[46:47]
	v_add_f32_e32 v42, 1.0, v42
	v_rcp_f32_e32 v46, v42
	v_add_f32_e32 v42, 1.0, v62
	v_rcp_f32_e32 v47, v42
	v_lshlrev_b32_e32 v42, 16, v43
	v_mul_f32_e32 v62, 0x3d372713, v42
	v_mul_f32_e32 v62, v62, v42
	v_mov_b32_e32 v63, v42
	v_and_b32_e32 v43, 0xffff0000, v43
	v_fmac_f32_e32 v63, v62, v63
	v_mul_f32_e32 v62, 0x3f4c422a, v63
	v_mul_f32_e32 v63, 0x3d372713, v43
	v_mul_f32_e32 v63, v63, v43
	v_mov_b32_e32 v64, v43
	v_fmac_f32_e32 v64, v63, v64
	v_add_f32_e32 v62, v62, v62
	v_mul_f32_e32 v63, 0x3f4c422a, v64
	v_mul_f32_e32 v62, 0xbfb8aa3b, v62
	v_add_f32_e32 v63, v63, v63
	v_exp_f32_e32 v62, v62
	v_mul_f32_e32 v63, 0xbfb8aa3b, v63
	v_exp_f32_e32 v63, v63
	v_pk_mul_f32 v[46:47], v[46:47], v[60:61]
	v_add_f32_e32 v60, 1.0, v62
	v_lshlrev_b32_e32 v62, 16, v36
	v_add_f32_e32 v61, 1.0, v63
	v_and_b32_e32 v63, 0xffff0000, v36
	v_mul_f32_e32 v36, 0x3d372713, v62
	v_mul_f32_e32 v36, v36, v62
	v_mov_b32_e32 v64, v62
	v_fmac_f32_e32 v64, v36, v64
	v_mul_f32_e32 v36, 0x3f4c422a, v64
	v_mul_f32_e32 v64, 0x3d372713, v63
	v_mul_f32_e32 v64, v64, v63
	v_mov_b32_e32 v65, v63
	v_fmac_f32_e32 v65, v64, v65
	v_add_f32_e32 v36, v36, v36
	v_mul_f32_e32 v64, 0x3f4c422a, v65
	v_mul_f32_e32 v36, 0xbfb8aa3b, v36
	v_add_f32_e32 v64, v64, v64
	v_exp_f32_e32 v36, v36
	v_mul_f32_e32 v64, 0xbfb8aa3b, v64
	v_exp_f32_e32 v65, v64
	v_rcp_f32_e32 v60, v60
	v_rcp_f32_e32 v61, v61
	v_add_f32_e32 v36, 1.0, v36
	v_rcp_f32_e32 v64, v36
	v_add_f32_e32 v36, 1.0, v65
	v_rcp_f32_e32 v65, v36
	v_pk_mul_f32 v[42:43], v[60:61], v[42:43]
	v_lshlrev_b32_e32 v36, 16, v37
	s_waitcnt lgkmcnt(0)
	v_pk_mul_f32 v[42:43], v[42:43], v[50:51]
	v_mul_f32_e32 v50, 0x3d372713, v36
	v_mul_f32_e32 v50, v50, v36
	v_mov_b32_e32 v51, v36
	v_and_b32_e32 v37, 0xffff0000, v37
	v_fmac_f32_e32 v51, v50, v51
	v_mul_f32_e32 v50, 0x3f4c422a, v51
	v_mul_f32_e32 v51, 0x3d372713, v37
	v_mul_f32_e32 v51, v51, v37
	v_mov_b32_e32 v60, v37
	v_fmac_f32_e32 v60, v51, v60
	v_mul_f32_e32 v51, 0x3f4c422a, v60
	v_add_f32_e32 v50, v50, v50
	v_add_f32_e32 v51, v51, v51
	v_mul_f32_e32 v50, 0xbfb8aa3b, v50
	v_mul_f32_e32 v51, 0xbfb8aa3b, v51
	ds_read_b128 v[52:55], v137 offset:32
	ds_read_b128 v[56:59], v137 offset:48
	v_exp_f32_e32 v50, v50
	v_exp_f32_e32 v51, v51
	v_pk_mul_f32 v[46:47], v[46:47], v[48:49]
	v_pk_mul_f32 v[48:49], v[64:65], v[62:63]
	v_add_f32_e32 v50, 1.0, v50
	s_waitcnt lgkmcnt(1)
	v_pk_mul_f32 v[48:49], v[48:49], v[52:53]
	v_add_f32_e32 v51, 1.0, v51
	v_lshlrev_b32_e32 v52, 16, v38
	v_rcp_f32_e32 v50, v50
	v_rcp_f32_e32 v51, v51
	v_and_b32_e32 v53, 0xffff0000, v38
	v_mul_f32_e32 v38, 0x3d372713, v52
	v_mul_f32_e32 v38, v38, v52
	v_mov_b32_e32 v60, v52
	v_fmac_f32_e32 v60, v38, v60
	v_mul_f32_e32 v38, 0x3f4c422a, v60
	v_mul_f32_e32 v60, 0x3d372713, v53
	v_mul_f32_e32 v60, v60, v53
	v_mov_b32_e32 v61, v53
	v_pk_mul_f32 v[36:37], v[50:51], v[36:37]
	v_lshlrev_b32_e32 v50, 16, v39
	v_fmac_f32_e32 v61, v60, v61
	v_and_b32_e32 v51, 0xffff0000, v39
	v_mul_f32_e32 v39, 0x3d372713, v50
	v_mul_f32_e32 v60, 0x3f4c422a, v61
	v_mul_f32_e32 v39, v39, v50
	v_mov_b32_e32 v61, v50
	v_fmac_f32_e32 v61, v39, v61
	v_mul_f32_e32 v39, 0x3f4c422a, v61
	v_add_f32_e32 v39, v39, v39
	v_mul_f32_e32 v39, 0xbfb8aa3b, v39
	v_exp_f32_e32 v61, v39
	v_mul_f32_e32 v39, 0x3d372713, v51
	v_mul_f32_e32 v39, v39, v51
	v_mov_b32_e32 v62, v51
	v_fmac_f32_e32 v62, v39, v62
	v_add_f32_e32 v38, v38, v38
	v_add_f32_e32 v60, v60, v60
	v_mul_f32_e32 v39, 0x3f4c422a, v62
	v_mul_f32_e32 v38, 0xbfb8aa3b, v38
	v_mul_f32_e32 v60, 0xbfb8aa3b, v60
	v_add_f32_e32 v39, v39, v39
	v_exp_f32_e32 v38, v38
	v_exp_f32_e32 v60, v60
	v_mul_f32_e32 v39, 0xbfb8aa3b, v39
	v_exp_f32_e32 v62, v39
	v_add_f32_e32 v38, 1.0, v38
	v_add_f32_e32 v60, 1.0, v60
	v_rcp_f32_e32 v38, v38
	v_rcp_f32_e32 v39, v60
	v_add_f32_e32 v60, 1.0, v61
	v_add_f32_e32 v61, 1.0, v62
	v_rcp_f32_e32 v60, v60
	v_rcp_f32_e32 v61, v61
	v_pk_mul_f32 v[54:55], v[36:37], v[54:55]
	v_pk_mul_f32 v[36:37], v[38:39], v[52:53]
	v_lshl_add_u64 v[2:3], v[2:3], 1, s[18:19]
	s_waitcnt lgkmcnt(0)
	v_pk_mul_f32 v[52:53], v[36:37], v[56:57]
	v_pk_mul_f32 v[36:37], v[60:61], v[50:51]
	v_lshl_add_u64 v[2:3], v[2:3], 0, v[0:1]
	v_pk_mul_f32 v[50:51], v[36:37], v[58:59]
	v_cvt_pk_bf16_f32 v36, v40, v41
	v_cvt_pk_bf16_f32 v37, v44, v45
	v_cvt_pk_bf16_f32 v38, v46, v47
	v_cvt_pk_bf16_f32 v39, v42, v43
	global_store_dwordx4 v[2:3], v[36:39], off
	s_nop 1
	v_cvt_pk_bf16_f32 v36, v48, v49
	v_cvt_pk_bf16_f32 v37, v54, v55
	v_cvt_pk_bf16_f32 v38, v52, v53
	v_cvt_pk_bf16_f32 v39, v50, v51
	global_store_dwordx4 v[2:3], v[36:39], off offset:16
	s_barrier
	s_mov_b32 s20, s98
	s_waitcnt lgkmcnt(0)
	s_add_i32 s7, s7, s20
	s_cmpk_gt_i32 s7, 0x7ff
	s_cbranch_scc1 .LBB0_153

; __device__ __forceinline__ u32x4 pack8(const float* f) { u32x4 w; w.x = cvt_pk_bf16(f[0], f[1]); w.y = cvt_pk_bf16(f[2], f[3]); w.z = cvt_pk_bf16(f[4], f[5]); w.w = cvt_pk_bf16(f[6], f[7]); return w; }
; __device__ __forceinline__ void gdn_prep(KA a, int layer, unsigned char* lds, const int tid_, const int bid_) {
;     ...
;         {
;             float xu[16], xw[16];
; #pragma unroll
;             for (int q = 0; q < 4; ++q) { const f32x4 u4 = *(const f32x4*)(RHS + tl * 260 + 16 * sub + 4 * q), w4 = *(const f32x4*)(RHS + tl * 260 + 128 + 16 * sub + 4 * q);
;                 xu[4 * q] = u4.x; xu[4 * q + 1] = u4.y; xu[4 * q + 2] = u4.z; xu[4 * q + 3] = u4.w; xw[4 * q] = w4.x; xw[4 * q + 1] = w4.y; xw[4 * q + 2] = w4.z; xw[4 * q + 3] = w4.w; }
;             bf16_t* du = (bf16_t*)(ws + WS_U) + (size_t)tg * 1024 + h * 128 + 16 * sub; bf16_t* dw = (bf16_t*)(ws + WS_W) + (size_t)tg * 1024 + h * 128 + 16 * sub;
;             *(u32x4*)du = pack8(xu); *(u32x4*)(du + 8) = pack8(xu + 8); *(u32x4*)dw = pack8(xw); *(u32x4*)(dw + 8) = pack8(xw + 8);
; #pragma unroll
;             for (int r = 0; r < 2; ++r) { const int idx = tid + 512 * r; *(u32x4*)((bf16_t*)(ws + WS_KDT) + (size_t)item * 8192 + idx * 8) = *(const u32x4*)(KDTs + (idx >> 3) * 144 + (((idx & 7) ^ ((idx >> 7) & 7)) * 16)); }
;         }
;         __syncthreads();
.LBB0_208:
	s_or_b64 exec, exec, s[90:91]
	v_lshlrev_b64 v[36:37], 10, v[106:107]
	v_lshlrev_b64 v[36:37], 1, v[36:37]
	s_waitcnt lgkmcnt(0)
	s_barrier
	ds_read_b128 v[4:7], v153 offset:52224
	ds_read_b128 v[8:11], v153 offset:52240
	ds_read_b128 v[12:15], v153 offset:52256
	ds_read_b128 v[16:19], v153 offset:52272
	ds_read_b128 v[20:23], v153 offset:52736
	ds_read_b128 v[24:27], v153 offset:52752
	ds_read_b128 v[28:31], v153 offset:52768
	ds_read_b128 v[32:35], v153 offset:52784
	v_lshl_add_u64 v[38:39], s[12:13], 0, v[36:37]
	v_lshl_add_u64 v[38:39], v[38:39], 0, s[88:89]
	v_lshl_add_u64 v[38:39], v[38:39], 0, v[0:1]
	v_lshl_add_u64 v[36:37], s[14:15], 0, v[36:37]
	s_waitcnt lgkmcnt(7)
	v_cvt_pk_bf16_f32 v4, v4, v5
	v_cvt_pk_bf16_f32 v5, v6, v7
	s_waitcnt lgkmcnt(6)
	v_cvt_pk_bf16_f32 v6, v8, v9
	v_cvt_pk_bf16_f32 v7, v10, v11
	v_lshl_add_u64 v[36:37], v[36:37], 0, s[88:89]
	global_store_dwordx4 v[38:39], v[4:7], off
	v_lshl_add_u64 v[36:37], v[36:37], 0, v[0:1]
	ds_read_b128 v[8:11], v180
	s_waitcnt lgkmcnt(6)
	v_cvt_pk_bf16_f32 v4, v12, v13
	v_cvt_pk_bf16_f32 v5, v14, v15
	s_waitcnt lgkmcnt(5)
	v_cvt_pk_bf16_f32 v6, v16, v17
	v_cvt_pk_bf16_f32 v7, v18, v19
	global_store_dwordx4 v[38:39], v[4:7], off offset:16
	v_lshlrev_b64 v[2:3], 14, v[2:3]
	v_lshl_add_u64 v[2:3], s[16:17], 0, v[2:3]
	s_waitcnt lgkmcnt(4)
	v_cvt_pk_bf16_f32 v4, v20, v21
	v_cvt_pk_bf16_f32 v5, v22, v23
	s_waitcnt lgkmcnt(3)
	v_cvt_pk_bf16_f32 v6, v24, v25
	v_cvt_pk_bf16_f32 v7, v26, v27
	global_store_dwordx4 v[36:37], v[4:7], off
	v_lshl_add_u64 v[12:13], v[102:103], 1, v[2:3]
	v_lshl_add_u64 v[2:3], v[104:105], 1, v[2:3]
	s_waitcnt lgkmcnt(2)
	v_cvt_pk_bf16_f32 v4, v28, v29
	v_cvt_pk_bf16_f32 v5, v30, v31
	s_waitcnt lgkmcnt(1)
	v_cvt_pk_bf16_f32 v6, v32, v33
	v_cvt_pk_bf16_f32 v7, v34, v35
	global_store_dwordx4 v[36:37], v[4:7], off offset:16
	ds_read_b128 v[4:7], v179
	s_mov_b64 s[92:93], s[34:35]
	s_waitcnt lgkmcnt(0)
	global_store_dwordx4 v[12:13], v[4:7], off
	global_store_dwordx4 v[2:3], v[8:11], off
	s_barrier
	s_mov_b32 s19, s99
	s_mov_b32 s31, s98
	s_waitcnt lgkmcnt(0)
	s_lshr_b32 s19, s19, 16
	s_cmp_lg_u32 s19, 0
	s_cselect_b64 s[20:21], -1, 0
	s_cmp_lg_u64 s[20:21], 0
	s_addc_u32 s18, s31, s18
	s_cmpk_lt_i32 s18, 0x800
	s_cbranch_scc0 .LBB0_223

; #define PREP_LOAD(p) do { _Pragma("unroll") for (int j = 0; j < 4; ++j) { const int rowi = (s - 3 + j >= 0) ? tg - 3 + j : tg; const bf16_t* row = QKV + (size_t)rowi * 3072 + (p) * 1024 + h * 128 + 16 * sub; \
;                 xr[(p) & 1][j][0] = *(const u32x4*)row; xr[(p) & 1][j][1] = *(const u32x4*)(row + 8); } } while (0)
; __device__ __forceinline__ void gdn_prep(KA a, int layer, unsigned char* lds, const int tid_, const int bid_) {
;     ...
;     for (int item = bid_; item < 2048; item += gridDim.x) {
;         const int c = item >> 3, h = item & 7, tg0 = c * 64;
;         const int tg = tg0 + tl, s = tg & (SEQ_ - 1);
;         if (h != h_loaded) {
;             if (tid < 384) { const int pj = tid >> 5, q4 = tid & 31; *(f32x4*)(cwl + pj * 128 + q4 * 4) = *(const f32x4*)(cw + (pj & 3) * 3072 + (pj >> 2) * 1024 + h * 128 + q4 * 4); }
;             h_loaded = h;
;             __syncthreads();
;         }
;         u32x4 xr[2][4][2];
;     ...
;         PREP_LOAD(0); PREP_LOAD(1);
;         if (wave == 0) {
;             float g = g_nx; const float bt = b_nx;
;             const int nit = item + gridDim.x;
;             if (nit < 2048) { g_nx = G[(size_t)((nit >> 3) * 64 + lane) * 8 + (nit & 7)]; b_nx = BETA[(size_t)((nit >> 3) * 64 + lane) * 8 + (nit & 7)]; }
; #pragma unroll
;             for (int o = 1; o < 64; o <<= 1) { const float t = __shfl_up(g, o); if (lane >= o) g += t; }
;             gcs[lane] = g; bts[lane] = bt;
;             if (lane == 63) ((float*)(ws + WS_EGL))[item] = expf(g);
.LBB0_213:
	s_lshl_b32 s19, s18, 3
	s_andn2_b32 s19, s19, 63
	v_add_u32_e32 v106, s19, v144
	v_and_b32_e32 v4, 0xfff, v106
	v_add_u32_e32 v5, -3, v106
	s_lshl_b32 s88, s31, 8
	v_cmp_gt_u32_e64 s[90:91], 3, v4
	v_lshl_add_u64 v[2:3], v[96:97], 0, s[88:89]
	v_mov_b64_e32 v[8:9], s[8:9]
	v_cndmask_b32_e64 v5, v5, v106, s[90:91]
	v_mad_i64_i32 v[6:7], s[20:21], v5, s26, v[2:3]
	global_load_dwordx4 v[54:57], v[6:7], off offset:16
	global_load_dwordx4 v[70:73], v[6:7], off
	v_add_u32_e32 v6, -2, v106
	v_cmp_gt_u32_e64 s[90:91], 2, v4
	v_mad_i64_i32 v[108:109], s[20:21], v106, s26, v[8:9]
	s_nop 0
	v_cndmask_b32_e64 v10, v6, v106, s[90:91]
	v_cmp_ne_u32_e64 s[90:91], 0, v4
	v_mad_i64_i32 v[6:7], s[20:21], v10, s26, v[2:3]
	s_nop 0
	v_subbrev_co_u32_e64 v12, s[90:91], 0, v106, s[90:91]
	global_load_dwordx4 v[58:61], v[6:7], off offset:16
	global_load_dwordx4 v[74:77], v[6:7], off
	v_mad_i64_i32 v[6:7], s[20:21], v12, s26, v[2:3]
	v_mad_i64_i32 v[2:3], s[20:21], v106, s26, v[2:3]
	global_load_dwordx4 v[62:65], v[6:7], off offset:16
	global_load_dwordx4 v[78:81], v[6:7], off
	global_load_dwordx4 v[50:53], v[2:3], off offset:16
	global_load_dwordx4 v[66:69], v[2:3], off
	v_mad_i64_i32 v[2:3], s[20:21], v5, s26, v[8:9]
	v_lshl_add_u64 v[6:7], v[2:3], 0, s[88:89]
	v_lshl_add_u64 v[6:7], v[6:7], 0, v[0:1]
	global_load_dwordx4 v[18:21], v[6:7], off offset:2064
	global_load_dwordx4 v[34:37], v[6:7], off offset:2048
	v_mad_i64_i32 v[6:7], s[20:21], v10, s26, v[8:9]
	v_lshl_add_u64 v[10:11], v[6:7], 0, s[88:89]
	v_lshl_add_u64 v[10:11], v[10:11], 0, v[0:1]
	v_mad_i64_i32 v[116:117], s[20:21], v12, s26, v[8:9]
	global_load_dwordx4 v[22:25], v[10:11], off offset:2064
	global_load_dwordx4 v[38:41], v[10:11], off offset:2048
	v_lshl_add_u64 v[10:11], v[116:117], 0, s[88:89]
	v_lshl_add_u64 v[8:9], v[108:109], 0, s[88:89]
	v_lshl_add_u64 v[10:11], v[10:11], 0, v[0:1]
	v_lshl_add_u64 v[8:9], v[8:9], 0, v[0:1]
	global_load_dwordx4 v[26:29], v[10:11], off offset:2064
	global_load_dwordx4 v[42:45], v[10:11], off offset:2048
	global_load_dwordx4 v[30:33], v[8:9], off offset:2064
	global_load_dwordx4 v[46:49], v[8:9], off offset:2048
	s_mov_b64 s[34:35], s[92:93]
	s_and_saveexec_b64 s[92:93], s[40:41]
	s_cbranch_execz .LBB0_219
	s_mov_b32 s19, s99
	s_mov_b32 s88, s98
	s_waitcnt vmcnt(16)
	v_mov_b32_e32 v8, v147
	v_mov_b32_e32 v5, v157
	s_waitcnt lgkmcnt(0)
	s_lshr_b32 s19, s19, 16
	s_cmp_lg_u32 s19, 0
	s_cselect_b64 s[20:21], -1, 0
	s_cmp_lg_u64 s[20:21], 0
	s_addc_u32 s19, s88, s18
	s_cmpk_gt_i32 s19, 0x7ff
	s_cbranch_scc1 .LBB0_216
	s_lshl_b32 s20, s19, 3
	s_andn2_b32 s20, s20, 63
	v_or_b32_e32 v8, s20, v198
	v_ashrrev_i32_e32 v9, 31, v8
	s_and_b32 s19, s19, 7
	v_lshlrev_b64 v[8:9], 5, v[8:9]
	v_lshl_or_b32 v8, s19, 2, v8
	v_lshl_add_u64 v[10:11], s[4:5], 0, v[8:9]
	v_lshl_add_u64 v[8:9], s[42:43], 0, v[8:9]
	global_load_dword v5, v[10:11], off
	s_nop 0
	global_load_dword v8, v[8:9], off

; __device__ __forceinline__ void unpack8(const u32x4 w, float* f) { f[0] = bflo(w.x); f[1] = bfhi(w.x); f[2] = bflo(w.y); f[3] = bfhi(w.y); f[4] = bflo(w.z); f[5] = bfhi(w.z); f[6] = bflo(w.w); f[7] = bfhi(w.w); }
; __device__ __forceinline__ u32x4 pack8(const float* f) { u32x4 w; w.x = cvt_pk_bf16(f[0], f[1]); w.y = cvt_pk_bf16(f[2], f[3]); w.z = cvt_pk_bf16(f[4], f[5]); w.w = cvt_pk_bf16(f[6], f[7]); return w; }
; __device__ __forceinline__ float gelu_tanh(float x) { const float u = 0.7978845608028654f * (x + 0.044715f * x * x * x); return x * sigmoidf_(2.0f * u); }
; template <bool P3>
; __device__ __forceinline__ void lru_pass(KA a, int layer, unsigned char* lds, const int tid_, const int bid_) {
;     ...
;         __syncthreads();
;         if (P3) {
;             float y[16], o[16]; unpack8(yr0, y); unpack8(yr1, y + 8);
; #pragma unroll
;             for (int e = 0; e < 16; ++e) o[e] = XCF[tl * 132 + 16 * sub + e] * gelu_tanh(y[e]);
;             bf16_t* dst = (bf16_t*)(ws + WS_OL) + (size_t)tg * 1024 + ch0;
;             *(u32x4*)dst = pack8(o); *(u32x4*)(dst + 8) = pack8(o + 8);
;             __syncthreads();
;         }
;     }
; }
.LBB0_226:
	s_or_b64 exec, exec, s[18:19]
	s_barrier
	s_mov_b32 s16, s98
	s_waitcnt lgkmcnt(0)
	s_add_i32 s7, s7, s16
	s_cmpk_gt_i32 s7, 0x7ff
	s_cbranch_scc1 .LBB0_239

; #define PG8_STAGE(bufoff, gbase, voff) do { _Pragma("unroll") for (int _i = 0; _i < 2; ++_i) \
;         __builtin_amdgcn_global_load_lds((const unsigned*)((const char*)(gbase) + (voff)[_i]), (LAS unsigned*)(lds + (bufoff) + ldsw + _i * 8192), 16, 0, 0); } while (0)
; #define PG8_WAIT_V(n) asm volatile("s_waitcnt vmcnt(" #n ")" ::: "memory")
; #define PG8_BAR __builtin_amdgcn_s_barrier()
; template <class Epi, class Sched, bool ALIGN_EPI = false, bool SP2 = false>
; __device__ __forceinline__ void gemm_phase(LAS unsigned char* lds, const Gemm g, const Sched& S, const Epi& E, const int tid_) {
;     ...
;     if constexpr (SP2) {
;         PG8_STAGE(PG8_SB(0, 0), cB, voffB); PG8_STAGE(PG8_SB(0, 1), cB + hstep, voffB); PG8_STAGE(PG8_SA(0, 0), cA, voffA); PG8_STAGE(PG8_SA(0, 1), cA + hstep, voffA);
;         if (wr == 1) PG8_BAR;
;         PG8_WAIT_V(2); PG8_BAR;
;         PG8_STAGE(PG8_SB(1, 0), cB + kstep, voffB); PG8_STAGE(PG8_SA(1, 0), cA + kstep, voffA); PG8_STAGE(PG8_SB(1, 1), cB + hstep + kstep, voffB);
;         PG8_WAIT_V(6); PG8_BAR;
.LBB0_247:
	s_lshl_b32 s12, s12, 5
	s_and_b32 s20, s12, 0x60
	s_add_i32 m0, s57, 0x18000
	v_lshl_add_u64 v[8:9], v[8:9], 0, s[96:97]
	s_lshl_b32 s14, s11, 13
	s_lshl_b32 s15, s20, 7
	s_nop 0
	global_load_lds_dwordx4 v[8:9], off
	v_lshl_add_u64 v[6:7], v[6:7], 0, s[96:97]
	s_add_i32 m0, s57, 0x1a000
	s_add_i32 s67, s57, 0x8000
	s_add_i32 s68, s57, 0xa000
	global_load_lds_dwordx4 v[6:7], off
	v_lshl_add_u64 v[2:3], v[2:3], 0, s[96:97]
	s_mov_b32 m0, s67
	s_add_u32 s12, s58, 0x80080
	global_load_lds_dwordx4 v[2:3], off
	v_lshl_add_u64 v[2:3], v[4:5], 0, s[96:97]
	s_mov_b32 m0, s68
	s_addc_u32 s13, s59, 0
	global_load_lds_dwordx4 v[2:3], off
	s_add_i32 m0, s57, 0x1c000
	v_lshl_add_u64 v[2:3], s[12:13], 0, v[0:1]
	global_load_lds_dwordx4 v[2:3], off
	v_lshl_add_u64 v[2:3], s[12:13], 0, v[134:135]
	s_add_i32 m0, s57, 0x1e000
	s_cmpk_lt_u32 s10, 0x100
	global_load_lds_dwordx4 v[2:3], off
	s_waitcnt vmcnt(8)
	s_barrier
	v_lshrrev_b32_e32 v3, 1, v198
	v_and_b32_e32 v3, 24, v3
	v_and_b32_e32 v2, 15, v198
	v_lshlrev_b32_e32 v4, 1, v3
	v_lshl_or_b32 v144, s11, 6, v2
	v_lshl_or_b32 v2, v2, 6, v4
	v_lshlrev_b32_e32 v4, 2, v198
	v_and_b32_e32 v4, 32, v4
	s_cselect_b64 s[10:11], -1, 0
	s_add_u32 s12, s4, 0x19800000
	v_bitop3_b32 v5, v2, s14, v4 bitop3:0xde
	v_bitop3_b32 v145, s15, v2, v4 bitop3:0xf6
	s_addc_u32 s13, s5, 0
	v_lshlrev_b32_e32 v2, 15, v10
	s_add_u32 s14, s4, 0x17800000
	v_and_b32_e32 v2, 0xffff0000, v2
	s_addc_u32 s15, s5, 0
	v_or_b32_e32 v146, s20, v3
	v_lshl_add_u32 v2, v11, 12, v2
	v_and_b32_e32 v3, 1, v10
	s_add_u32 s16, s4, 0x15800000
	v_lshl_or_b32 v2, v3, 6, v2
	s_addc_u32 s17, s5, 0
	v_lshl_add_u32 v136, v12, 1, v2
	v_lshlrev_b32_e32 v2, 15, v13
	s_add_u32 s18, s4, 0x13800000
	v_and_b32_e32 v2, 0xffff0000, v2
	s_waitcnt vmcnt(6)
	s_addc_u32 s19, s5, 0
	v_lshl_add_u32 v2, v14, 12, v2
	v_and_b32_e32 v3, 1, v13
	s_add_u32 s44, s4, 0xd800000
	v_lshl_or_b32 v2, v3, 6, v2
	s_addc_u32 s45, s5, 0
	s_waitcnt lgkmcnt(0)
	s_ashr_i32 s69, s66, 31
	s_ashr_i32 s70, s28, 31
	v_mov_b32_e32 v137, v1
	v_lshl_add_u32 v138, v15, 1, v2
	v_mov_b32_e32 v139, v1
	s_mov_b32 s71, 0
	s_waitcnt vmcnt(0)
	v_add_u32_e32 v147, 0, v5
	s_barrier
	s_branch .LBB0_250

; #define PG8_STAGE(bufoff, gbase, voff) do { _Pragma("unroll") for (int _i = 0; _i < 2; ++_i) \
;         __builtin_amdgcn_global_load_lds((const unsigned*)((const char*)(gbase) + (voff)[_i]), (LAS unsigned*)(lds + (bufoff) + ldsw + _i * 8192), 16, 0, 0); } while (0)
; #define PG8_WAIT_V(n) asm volatile("s_waitcnt vmcnt(" #n ")" ::: "memory")
; #define PG8_BAR __builtin_amdgcn_s_barrier()
; template <class Epi, class Sched, bool ALIGN_EPI = false, bool SP2 = false>
; __device__ __forceinline__ void gemm_phase(LAS unsigned char* lds, const Gemm g, const Sched& S, const Epi& E, const int tid_) {
;     ...
;     if constexpr (SP2) {
;         PG8_STAGE(PG8_SB(0, 0), cB, voffB); PG8_STAGE(PG8_SB(0, 1), cB + hstep, voffB); PG8_STAGE(PG8_SA(0, 0), cA, voffA); PG8_STAGE(PG8_SA(0, 1), cA + hstep, voffA);
;         if (wr == 1) PG8_BAR;
;         PG8_WAIT_V(2); PG8_BAR;
;         PG8_STAGE(PG8_SB(1, 0), cB + kstep, voffB); PG8_STAGE(PG8_SA(1, 0), cA + kstep, voffA); PG8_STAGE(PG8_SB(1, 1), cB + hstep + kstep, voffB);
;         PG8_WAIT_V(6); PG8_BAR;
.LBB0_349:
	v_bfe_u32 v18, v198, 4, 2
	v_and_b32_e32 v19, 15, v198
	v_lshlrev_b32_e32 v20, 4, v18
	v_lshl_or_b32 v156, s14, 6, v19
	v_lshl_or_b32 v19, v19, 6, v20
	v_lshlrev_b32_e32 v20, 2, v198
	s_sext_i32_i8 s20, s12
	s_lshl_b32 s12, s14, 13
	v_and_b32_e32 v20, 32, v20
	v_bitop3_b32 v21, v19, s12, v20 bitop3:0xde
	s_lshl_b32 s12, s15, 5
	s_and_b32 s16, s12, 0x60
	s_add_i32 m0, s45, 0x18000
	v_lshl_add_u64 v[8:9], v[8:9], 0, s[96:97]
	s_lshl_b32 s12, s16, 7
	s_nop 0
	global_load_lds_dwordx4 v[8:9], off
	v_lshl_add_u64 v[6:7], v[6:7], 0, s[96:97]
	s_add_i32 m0, s45, 0x1a000
	s_add_i32 s60, s45, 0x8000
	s_add_i32 s61, s45, 0xa000
	global_load_lds_dwordx4 v[6:7], off
	v_lshl_add_u64 v[2:3], v[2:3], 0, s[96:97]
	s_mov_b32 m0, s60
	s_add_u32 s14, s48, 0x200080
	global_load_lds_dwordx4 v[2:3], off
	v_lshl_add_u64 v[2:3], v[4:5], 0, s[96:97]
	s_mov_b32 m0, s61
	s_addc_u32 s15, s49, 0
	global_load_lds_dwordx4 v[2:3], off
	s_add_i32 m0, s45, 0x1c000
	v_lshl_add_u64 v[2:3], s[14:15], 0, v[0:1]
	global_load_lds_dwordx4 v[2:3], off
	v_lshl_add_u64 v[2:3], s[14:15], 0, v[142:143]
	s_add_i32 m0, s45, 0x1e000
	s_mov_b64 s[14:15], 0x200080
	global_load_lds_dwordx4 v[2:3], off
	s_waitcnt vmcnt(8)
	s_barrier
	v_lshlrev_b32_e32 v2, 16, v10
	v_and_b32_e32 v2, 0x7ffe0000, v2
	v_lshl_add_u32 v2, v11, 13, v2
	v_or_b32_e32 v2, v2, v12
	v_add_lshl_u32 v2, v2, v13, 1
	v_mov_b32_e32 v3, v1
	v_lshl_add_u64 v[144:145], v[2:3], 0, s[14:15]
	v_lshlrev_b32_e32 v2, 16, v14
	v_and_b32_e32 v2, 0x7ffe0000, v2
	v_lshl_add_u32 v2, v15, 13, v2
	s_waitcnt vmcnt(6)
	v_or_b32_e32 v2, v2, v16
	s_cmpk_lt_u32 s13, 0x100
	v_add_lshl_u32 v2, v2, v17, 1
	s_waitcnt vmcnt(0)
	v_bitop3_b32 v157, s12, v19, v20 bitop3:0xf6
	s_cselect_b64 s[12:13], -1, 0
	s_waitcnt lgkmcnt(0)
	s_ashr_i32 s62, s59, 31
	v_lshl_or_b32 v158, v18, 2, s16
	v_lshl_add_u64 v[146:147], v[2:3], 0, s[14:15]
	s_mov_b32 s63, 0
	v_add_u32_e32 v159, 0, v21
	s_barrier
	s_branch .LBB0_352

; __global__ void __launch_bounds__(512, 2) mega(Args a_) {
	.amdhsa_kernel _Z4mega4Args
		.amdhsa_group_segment_fixed_size 0
		.amdhsa_private_segment_fixed_size 0
		.amdhsa_kernarg_size 448
		.amdhsa_user_sgpr_count 2
		.amdhsa_user_sgpr_dispatch_ptr 0
		.amdhsa_user_sgpr_queue_ptr 0
		.amdhsa_user_sgpr_kernarg_segment_ptr 1
		.amdhsa_user_sgpr_dispatch_id 0
		.amdhsa_user_sgpr_kernarg_preload_length 0
		.amdhsa_user_sgpr_kernarg_preload_offset 0
		.amdhsa_user_sgpr_private_segment_size 0
		.amdhsa_uses_dynamic_stack 0
		.amdhsa_enable_private_segment 0
		.amdhsa_system_sgpr_workgroup_id_x 1
		.amdhsa_system_sgpr_workgroup_id_y 0
		.amdhsa_system_sgpr_workgroup_id_z 0
		.amdhsa_system_sgpr_workgroup_info 0
		.amdhsa_system_vgpr_workitem_id 2
		.amdhsa_next_free_vgpr 256
		.amdhsa_next_free_sgpr 100
		.amdhsa_accum_offset 256
		.amdhsa_reserve_vcc 1
		.amdhsa_float_round_mode_32 0
		.amdhsa_float_round_mode_16_64 0
		.amdhsa_float_denorm_mode_32 3
		.amdhsa_float_denorm_mode_16_64 3
		.amdhsa_dx10_clamp 1
		.amdhsa_ieee_mode 1
		.amdhsa_fp16_overflow 0
		.amdhsa_tg_split 0
		.amdhsa_exception_fp_ieee_invalid_op 0
		.amdhsa_exception_fp_denorm_src 0
		.amdhsa_exception_fp_ieee_div_zero 0
		.amdhsa_exception_fp_ieee_overflow 0
		.amdhsa_exception_fp_ieee_underflow 0
		.amdhsa_exception_fp_ieee_inexact 0
		.amdhsa_exception_int_div_zero 0
	.end_amdhsa_kernel

; __global__ void __launch_bounds__(512, 2) mega(Args a_) {
amdhsa.kernels:
  - .agpr_count:     0
    .args:
      - .offset:         0
        .size:           192
        .value_kind:     by_value
      - .offset:         192
        .size:           4
        .value_kind:     hidden_block_count_x
      - .offset:         196
        .size:           4
        .value_kind:     hidden_block_count_y
      - .offset:         200
        .size:           4
        .value_kind:     hidden_block_count_z
      - .offset:         204
        .size:           2
        .value_kind:     hidden_group_size_x
      - .offset:         206
        .size:           2
        .value_kind:     hidden_group_size_y
      - .offset:         208
        .size:           2
        .value_kind:     hidden_group_size_z
      - .offset:         210
        .size:           2
        .value_kind:     hidden_remainder_x
      - .offset:         212
        .size:           2
        .value_kind:     hidden_remainder_y
      - .offset:         214
        .size:           2
        .value_kind:     hidden_remainder_z
      - .offset:         232
        .size:           8
        .value_kind:     hidden_global_offset_x
      - .offset:         240
        .size:           8
        .value_kind:     hidden_global_offset_y
      - .offset:         248
        .size:           8
        .value_kind:     hidden_global_offset_z
      - .offset:         256
        .size:           2
        .value_kind:     hidden_grid_dims
      - .offset:         280
        .size:           8
        .value_kind:     hidden_multigrid_sync_arg
      - .offset:         312
        .size:           4
        .value_kind:     hidden_dynamic_lds_size
    .group_segment_fixed_size: 0
    .kernarg_segment_align: 8
    .kernarg_segment_size: 448
    .language:       OpenCL C
    .language_version:
      - 2
      - 0
    .max_flat_workgroup_size: 512
    .name:           _Z4mega4Args
    .private_segment_fixed_size: 0
    .sgpr_count:     106
    .sgpr_spill_count: 113
    .symbol:         _Z4mega4Args.kd
    .uniform_work_group_size: 1
    .uses_dynamic_stack: false
    .vgpr_count:     256
    .vgpr_spill_count: 0
    .wavefront_size: 64
